# P3 out-proj epilogue, full-K latent tiles: single writer per element, so load + v_mul + v_add + store replaces the float atomics (split-K ctx tiles keep atomics)
# speedup vs baseline: 1.0169x; 1.0169x over previous
; __device__ __forceinline__ void outproj_tile(const Params& p, char* smem, int l, int mt, int nt, int ks) {
;     ...
;   auto epi = [&](f32x4 (&acc)[8][4], int wr, int wc, int fr, int fq) {
;     const int row0 = mt * 256;
;     const int v = row0 < MLAT ? (row0 >> 13) : 2;
;     float* O = l == 0 ? XN : p.out;
;     float gv[4];
; #pragma unroll
;     for (int n = 0; n < 4; ++n) gv[n] = MODS[(l * 3 + v) * 6144 + 2048 + nt * 128 + wc * 64 + n * 16 + fr];
; #pragma unroll
;     for (int m = 0; m < 8; ++m)
; #pragma unroll
;       for (int j = 0; j < 4; ++j) {
;         int row = row0 + wr * 128 + m * 16 + fq * 4 + j;
;         float* orow = O + (size_t)row * 1024 + nt * 128 + wc * 64 + fr;
; #pragma unroll
;         for (int n = 0; n < 4; ++n) unsafeAtomicAdd(orow + n * 16, gv[n] * acc[m][n][j]);
;       }
.LBB0_1194:
	v_ashrrev_i32_e32 v3, 31, v2
	v_lshl_add_u64 v[2:3], v[2:3], 2, s[0:1]
	s_mov_b64 s[0:1], 0x18e00000
	s_waitcnt vmcnt(0)
	v_lshl_add_u64 v[134:135], v[2:3], 0, s[0:1]
	v_add_co_u32_e32 v2, vcc, 0x18e00000, v2
	global_load_dword v138, v[134:135], off offset:192
	global_load_dword v139, v[134:135], off offset:128
	global_load_dword v140, v[134:135], off offset:64
	v_addc_co_u32_e32 v3, vcc, 0, v3, vcc
	global_load_dword v141, v[2:3], off
	v_lshlrev_b32_e32 v2, 2, v157
	v_and_or_b32 v2, v2, 12, v133
	v_ashrrev_i32_e32 v3, 31, v2
	v_lshlrev_b64 v[134:135], 12, v[2:3]
	v_mov_b32_e32 v133, v1
	v_lshl_add_u64 v[134:135], s[12:13], 0, v[134:135]
	v_lshlrev_b64 v[132:133], 2, v[132:133]
	v_mov_b32_e32 v157, v1
	v_lshl_add_u64 v[136:137], v[134:135], 0, v[132:133]
	v_lshlrev_b64 v[134:135], 2, v[0:1]
	v_lshl_add_u64 v[142:143], v[136:137], 0, v[134:135]
	v_lshlrev_b64 v[136:137], 2, v[156:157]
	v_lshl_add_u64 v[142:143], v[142:143], 0, v[136:137]
	v_readlane_b32 s0, v239, 1
	v_readlane_b32 s1, v239, 2
	s_add_i32 s17, s17, s0
	s_waitcnt vmcnt(0) lgkmcnt(0)
	s_sub_i32 s6, s17, s0
	s_cmpk_lt_i32 s6, 0x200
	s_cbranch_scc0 .Lp3_atomic
	v_lshlrev_b32_e32 v142, 12, v2
	v_add3_u32 v142, v142, v132, v134
	v_add_u32_e32 v142, v142, v136
	v_add_u32_e32 v132, 0x0, v142
	v_add_u32_e32 v133, 0x1000, v142
	v_add_u32_e32 v134, 0x2000, v142
	v_add_u32_e32 v135, 0x3000, v142
	global_load_dword v240, v132, s[12:13]
	global_load_dword v241, v132, s[12:13] offset:64
	global_load_dword v242, v132, s[12:13] offset:128
	global_load_dword v243, v132, s[12:13] offset:192
	global_load_dword v244, v133, s[12:13]
	global_load_dword v245, v133, s[12:13] offset:64
	global_load_dword v246, v133, s[12:13] offset:128
	global_load_dword v247, v133, s[12:13] offset:192
	global_load_dword v248, v134, s[12:13]
	global_load_dword v249, v134, s[12:13] offset:64
	global_load_dword v250, v134, s[12:13] offset:128
	global_load_dword v251, v134, s[12:13] offset:192
	global_load_dword v252, v135, s[12:13]
	global_load_dword v253, v135, s[12:13] offset:64
	global_load_dword v254, v135, s[12:13] offset:128
	global_load_dword v255, v135, s[12:13] offset:192
	v_add_u32_e32 v136, 0x10000, v142
	v_add_u32_e32 v137, 0x11000, v142
	v_add_u32_e32 v143, 0x12000, v142
	v_add_u32_e32 v3, 0x13000, v142
	global_load_dword v144, v136, s[12:13]
	global_load_dword v145, v136, s[12:13] offset:64
	global_load_dword v146, v136, s[12:13] offset:128
	global_load_dword v147, v136, s[12:13] offset:192
	global_load_dword v148, v137, s[12:13]
	global_load_dword v149, v137, s[12:13] offset:64
	global_load_dword v150, v137, s[12:13] offset:128
	global_load_dword v151, v137, s[12:13] offset:192
	global_load_dword v152, v143, s[12:13]
	global_load_dword v153, v143, s[12:13] offset:64
	global_load_dword v154, v143, s[12:13] offset:128
	global_load_dword v155, v143, s[12:13] offset:192
	global_load_dword v232, v3, s[12:13]
	global_load_dword v233, v3, s[12:13] offset:64
	global_load_dword v234, v3, s[12:13] offset:128
	global_load_dword v235, v3, s[12:13] offset:192
	s_waitcnt vmcnt(16)
	v_mul_f32_e32 v128, v128, v141
	v_mul_f32_e32 v124, v124, v140
	v_mul_f32_e32 v120, v120, v139
	v_mul_f32_e32 v116, v116, v138
	v_mul_f32_e32 v129, v129, v141
	v_mul_f32_e32 v125, v125, v140
	v_mul_f32_e32 v121, v121, v139
	v_mul_f32_e32 v117, v117, v138
	v_mul_f32_e32 v130, v130, v141
	v_mul_f32_e32 v126, v126, v140
	v_mul_f32_e32 v122, v122, v139
	v_mul_f32_e32 v118, v118, v138
	v_mul_f32_e32 v131, v131, v141
	v_mul_f32_e32 v127, v127, v140
	v_mul_f32_e32 v123, v123, v139
	v_mul_f32_e32 v119, v119, v138
	v_add_f32_e32 v128, v240, v128
	v_add_f32_e32 v124, v241, v124
	v_add_f32_e32 v120, v242, v120
	v_add_f32_e32 v116, v243, v116
	v_add_f32_e32 v129, v244, v129
	v_add_f32_e32 v125, v245, v125
	v_add_f32_e32 v121, v246, v121
	v_add_f32_e32 v117, v247, v117
	v_add_f32_e32 v130, v248, v130
	v_add_f32_e32 v126, v249, v126
	v_add_f32_e32 v122, v250, v122
	v_add_f32_e32 v118, v251, v118
	v_add_f32_e32 v131, v252, v131
	v_add_f32_e32 v127, v253, v127
	v_add_f32_e32 v123, v254, v123
	v_add_f32_e32 v119, v255, v119
	v_add_u32_e32 v132, 0x20000, v142
	v_add_u32_e32 v133, 0x21000, v142
	v_add_u32_e32 v134, 0x22000, v142
	v_add_u32_e32 v135, 0x23000, v142
	global_load_dword v240, v132, s[12:13]
	global_load_dword v241, v132, s[12:13] offset:64
	global_load_dword v242, v132, s[12:13] offset:128
	global_load_dword v243, v132, s[12:13] offset:192
	global_load_dword v244, v133, s[12:13]
	global_load_dword v245, v133, s[12:13] offset:64
	global_load_dword v246, v133, s[12:13] offset:128
	global_load_dword v247, v133, s[12:13] offset:192
	global_load_dword v248, v134, s[12:13]
	global_load_dword v249, v134, s[12:13] offset:64
	global_load_dword v250, v134, s[12:13] offset:128
	global_load_dword v251, v134, s[12:13] offset:192
	global_load_dword v252, v135, s[12:13]
	global_load_dword v253, v135, s[12:13] offset:64
	global_load_dword v254, v135, s[12:13] offset:128
	global_load_dword v255, v135, s[12:13] offset:192
	s_waitcnt vmcnt(16)
; __device__ __forceinline__ void outproj_tile(const Params& p, char* smem, int l, int mt, int nt, int ks) {
;     ...
; #pragma unroll
;     for (int m = 0; m < 8; ++m)
; #pragma unroll
;       for (int j = 0; j < 4; ++j) {
;         int row = row0 + wr * 128 + m * 16 + fq * 4 + j;
;         float* orow = O + (size_t)row * 1024 + nt * 128 + wc * 64 + fr;
; #pragma unroll
;         for (int n = 0; n < 4; ++n) unsafeAtomicAdd(orow + n * 16, gv[n] * acc[m][n][j]);
	v_mul_f32_e32 v112, v112, v141
	v_mul_f32_e32 v108, v108, v140
	v_mul_f32_e32 v104, v104, v139
	v_mul_f32_e32 v100, v100, v138
	v_mul_f32_e32 v113, v113, v141
	v_mul_f32_e32 v109, v109, v140
	v_mul_f32_e32 v105, v105, v139
	v_mul_f32_e32 v101, v101, v138
	v_mul_f32_e32 v114, v114, v141
	v_mul_f32_e32 v110, v110, v140
	v_mul_f32_e32 v106, v106, v139
	v_mul_f32_e32 v102, v102, v138
	v_mul_f32_e32 v115, v115, v141
	v_mul_f32_e32 v111, v111, v140
	v_mul_f32_e32 v107, v107, v139
	v_mul_f32_e32 v103, v103, v138
	v_add_f32_e32 v112, v144, v112
	v_add_f32_e32 v108, v145, v108
	v_add_f32_e32 v104, v146, v104
	v_add_f32_e32 v100, v147, v100
	v_add_f32_e32 v113, v148, v113
	v_add_f32_e32 v109, v149, v109
	v_add_f32_e32 v105, v150, v105
	v_add_f32_e32 v101, v151, v101
	v_add_f32_e32 v114, v152, v114
	v_add_f32_e32 v110, v153, v110
	v_add_f32_e32 v106, v154, v106
	v_add_f32_e32 v102, v155, v102
	v_add_f32_e32 v115, v232, v115
	v_add_f32_e32 v111, v233, v111
	v_add_f32_e32 v107, v234, v107
	v_add_f32_e32 v103, v235, v103
	v_add_u32_e32 v136, 0x30000, v142
	v_add_u32_e32 v137, 0x31000, v142
	v_add_u32_e32 v143, 0x32000, v142
	v_add_u32_e32 v3, 0x33000, v142
	global_load_dword v144, v136, s[12:13]
	global_load_dword v145, v136, s[12:13] offset:64
	global_load_dword v146, v136, s[12:13] offset:128
	global_load_dword v147, v136, s[12:13] offset:192
	global_load_dword v148, v137, s[12:13]
	global_load_dword v149, v137, s[12:13] offset:64
	global_load_dword v150, v137, s[12:13] offset:128
	global_load_dword v151, v137, s[12:13] offset:192
	global_load_dword v152, v143, s[12:13]
	global_load_dword v153, v143, s[12:13] offset:64
	global_load_dword v154, v143, s[12:13] offset:128
	global_load_dword v155, v143, s[12:13] offset:192
	global_load_dword v232, v3, s[12:13]
	global_load_dword v233, v3, s[12:13] offset:64
	global_load_dword v234, v3, s[12:13] offset:128
	global_load_dword v235, v3, s[12:13] offset:192
	s_waitcnt vmcnt(16)
	v_mul_f32_e32 v96, v96, v141
	v_mul_f32_e32 v92, v92, v140
	v_mul_f32_e32 v88, v88, v139
	v_mul_f32_e32 v84, v84, v138
	v_mul_f32_e32 v97, v97, v141
	v_mul_f32_e32 v93, v93, v140
	v_mul_f32_e32 v89, v89, v139
	v_mul_f32_e32 v85, v85, v138
	v_mul_f32_e32 v98, v98, v141
	v_mul_f32_e32 v94, v94, v140
	v_mul_f32_e32 v90, v90, v139
	v_mul_f32_e32 v86, v86, v138
	v_mul_f32_e32 v99, v99, v141
	v_mul_f32_e32 v95, v95, v140
	v_mul_f32_e32 v91, v91, v139
	v_mul_f32_e32 v87, v87, v138
	v_add_f32_e32 v96, v240, v96
	v_add_f32_e32 v92, v241, v92
	v_add_f32_e32 v88, v242, v88
	v_add_f32_e32 v84, v243, v84
	v_add_f32_e32 v97, v244, v97
	v_add_f32_e32 v93, v245, v93
	v_add_f32_e32 v89, v246, v89
	v_add_f32_e32 v85, v247, v85
	v_add_f32_e32 v98, v248, v98
	v_add_f32_e32 v94, v249, v94
	v_add_f32_e32 v90, v250, v90
	v_add_f32_e32 v86, v251, v86
	v_add_f32_e32 v99, v252, v99
	v_add_f32_e32 v95, v253, v95
	v_add_f32_e32 v91, v254, v91
	v_add_f32_e32 v87, v255, v87
	v_add_u32_e32 v132, 0x40000, v142
	v_add_u32_e32 v133, 0x41000, v142
	v_add_u32_e32 v134, 0x42000, v142
	v_add_u32_e32 v135, 0x43000, v142
	global_load_dword v240, v132, s[12:13]
	global_load_dword v241, v132, s[12:13] offset:64
	global_load_dword v242, v132, s[12:13] offset:128
	global_load_dword v243, v132, s[12:13] offset:192
	global_load_dword v244, v133, s[12:13]
	global_load_dword v245, v133, s[12:13] offset:64
	global_load_dword v246, v133, s[12:13] offset:128
	global_load_dword v247, v133, s[12:13] offset:192
	global_load_dword v248, v134, s[12:13]
	global_load_dword v249, v134, s[12:13] offset:64
	global_load_dword v250, v134, s[12:13] offset:128
	global_load_dword v251, v134, s[12:13] offset:192
	global_load_dword v252, v135, s[12:13]
	global_load_dword v253, v135, s[12:13] offset:64
	global_load_dword v254, v135, s[12:13] offset:128
	global_load_dword v255, v135, s[12:13] offset:192
	s_waitcnt vmcnt(16)
	v_mul_f32_e32 v80, v80, v141
	v_mul_f32_e32 v76, v76, v140
	v_mul_f32_e32 v72, v72, v139
	v_mul_f32_e32 v68, v68, v138
	v_mul_f32_e32 v81, v81, v141
	v_mul_f32_e32 v77, v77, v140
	v_mul_f32_e32 v73, v73, v139
	v_mul_f32_e32 v69, v69, v138
	v_mul_f32_e32 v82, v82, v141
	v_mul_f32_e32 v78, v78, v140
	v_mul_f32_e32 v74, v74, v139
	v_mul_f32_e32 v70, v70, v138
	v_mul_f32_e32 v83, v83, v141
	v_mul_f32_e32 v79, v79, v140
	v_mul_f32_e32 v75, v75, v139
	v_mul_f32_e32 v71, v71, v138
	v_add_f32_e32 v80, v144, v80
	v_add_f32_e32 v76, v145, v76
	v_add_f32_e32 v72, v146, v72
	v_add_f32_e32 v68, v147, v68
	v_add_f32_e32 v81, v148, v81
	v_add_f32_e32 v77, v149, v77
	v_add_f32_e32 v73, v150, v73
	v_add_f32_e32 v69, v151, v69
	v_add_f32_e32 v82, v152, v82
	v_add_f32_e32 v78, v153, v78
	v_add_f32_e32 v74, v154, v74
	v_add_f32_e32 v70, v155, v70
	v_add_f32_e32 v83, v232, v83
	v_add_f32_e32 v79, v233, v79
	v_add_f32_e32 v75, v234, v75
	v_add_f32_e32 v71, v235, v71
	v_add_u32_e32 v136, 0x50000, v142
	v_add_u32_e32 v137, 0x51000, v142
	v_add_u32_e32 v143, 0x52000, v142
	v_add_u32_e32 v3, 0x53000, v142
	global_load_dword v144, v136, s[12:13]
	global_load_dword v145, v136, s[12:13] offset:64
	global_load_dword v146, v136, s[12:13] offset:128
	global_load_dword v147, v136, s[12:13] offset:192
	global_load_dword v148, v137, s[12:13]
	global_load_dword v149, v137, s[12:13] offset:64
	global_load_dword v150, v137, s[12:13] offset:128
	global_load_dword v151, v137, s[12:13] offset:192
	global_load_dword v152, v143, s[12:13]
	global_load_dword v153, v143, s[12:13] offset:64
	global_load_dword v154, v143, s[12:13] offset:128
	global_load_dword v155, v143, s[12:13] offset:192
	global_load_dword v232, v3, s[12:13]
	global_load_dword v233, v3, s[12:13] offset:64
	global_load_dword v234, v3, s[12:13] offset:128
	global_load_dword v235, v3, s[12:13] offset:192
	s_waitcnt vmcnt(16)
; __device__ __forceinline__ void outproj_tile(const Params& p, char* smem, int l, int mt, int nt, int ks) {
;     ...
; #pragma unroll
;     for (int m = 0; m < 8; ++m)
; #pragma unroll
;       for (int j = 0; j < 4; ++j) {
;         int row = row0 + wr * 128 + m * 16 + fq * 4 + j;
;         float* orow = O + (size_t)row * 1024 + nt * 128 + wc * 64 + fr;
; #pragma unroll
;         for (int n = 0; n < 4; ++n) unsafeAtomicAdd(orow + n * 16, gv[n] * acc[m][n][j]);
	v_mul_f32_e32 v64, v64, v141
	v_mul_f32_e32 v60, v60, v140
	v_mul_f32_e32 v56, v56, v139
	v_mul_f32_e32 v52, v52, v138
	v_mul_f32_e32 v65, v65, v141
	v_mul_f32_e32 v61, v61, v140
	v_mul_f32_e32 v57, v57, v139
	v_mul_f32_e32 v53, v53, v138
	v_mul_f32_e32 v66, v66, v141
	v_mul_f32_e32 v62, v62, v140
	v_mul_f32_e32 v58, v58, v139
	v_mul_f32_e32 v54, v54, v138
	v_mul_f32_e32 v67, v67, v141
	v_mul_f32_e32 v63, v63, v140
	v_mul_f32_e32 v59, v59, v139
	v_mul_f32_e32 v55, v55, v138
	v_add_f32_e32 v64, v240, v64
	v_add_f32_e32 v60, v241, v60
	v_add_f32_e32 v56, v242, v56
	v_add_f32_e32 v52, v243, v52
	v_add_f32_e32 v65, v244, v65
	v_add_f32_e32 v61, v245, v61
	v_add_f32_e32 v57, v246, v57
	v_add_f32_e32 v53, v247, v53
	v_add_f32_e32 v66, v248, v66
	v_add_f32_e32 v62, v249, v62
	v_add_f32_e32 v58, v250, v58
	v_add_f32_e32 v54, v251, v54
	v_add_f32_e32 v67, v252, v67
	v_add_f32_e32 v63, v253, v63
	v_add_f32_e32 v59, v254, v59
	v_add_f32_e32 v55, v255, v55
	v_add_u32_e32 v132, 0x60000, v142
	v_add_u32_e32 v133, 0x61000, v142
	v_add_u32_e32 v134, 0x62000, v142
	v_add_u32_e32 v135, 0x63000, v142
	global_load_dword v240, v132, s[12:13]
	global_load_dword v241, v132, s[12:13] offset:64
	global_load_dword v242, v132, s[12:13] offset:128
	global_load_dword v243, v132, s[12:13] offset:192
	global_load_dword v244, v133, s[12:13]
	global_load_dword v245, v133, s[12:13] offset:64
	global_load_dword v246, v133, s[12:13] offset:128
	global_load_dword v247, v133, s[12:13] offset:192
	global_load_dword v248, v134, s[12:13]
	global_load_dword v249, v134, s[12:13] offset:64
	global_load_dword v250, v134, s[12:13] offset:128
	global_load_dword v251, v134, s[12:13] offset:192
	global_load_dword v252, v135, s[12:13]
	global_load_dword v253, v135, s[12:13] offset:64
	global_load_dword v254, v135, s[12:13] offset:128
	global_load_dword v255, v135, s[12:13] offset:192
	s_waitcnt vmcnt(16)
	v_mul_f32_e32 v48, v48, v141
	v_mul_f32_e32 v44, v44, v140
	v_mul_f32_e32 v40, v40, v139
	v_mul_f32_e32 v36, v36, v138
	v_mul_f32_e32 v49, v49, v141
	v_mul_f32_e32 v45, v45, v140
	v_mul_f32_e32 v41, v41, v139
	v_mul_f32_e32 v37, v37, v138
	v_mul_f32_e32 v50, v50, v141
	v_mul_f32_e32 v46, v46, v140
	v_mul_f32_e32 v42, v42, v139
	v_mul_f32_e32 v38, v38, v138
	v_mul_f32_e32 v51, v51, v141
	v_mul_f32_e32 v47, v47, v140
	v_mul_f32_e32 v43, v43, v139
	v_mul_f32_e32 v39, v39, v138
	v_add_f32_e32 v48, v144, v48
	v_add_f32_e32 v44, v145, v44
	v_add_f32_e32 v40, v146, v40
	v_add_f32_e32 v36, v147, v36
	v_add_f32_e32 v49, v148, v49
	v_add_f32_e32 v45, v149, v45
	v_add_f32_e32 v41, v150, v41
	v_add_f32_e32 v37, v151, v37
	v_add_f32_e32 v50, v152, v50
	v_add_f32_e32 v46, v153, v46
	v_add_f32_e32 v42, v154, v42
	v_add_f32_e32 v38, v155, v38
	v_add_f32_e32 v51, v232, v51
	v_add_f32_e32 v47, v233, v47
	v_add_f32_e32 v43, v234, v43
	v_add_f32_e32 v39, v235, v39
	v_add_u32_e32 v136, 0x70000, v142
	v_add_u32_e32 v137, 0x71000, v142
	v_add_u32_e32 v143, 0x72000, v142
	v_add_u32_e32 v3, 0x73000, v142
	global_load_dword v144, v136, s[12:13]
	global_load_dword v145, v136, s[12:13] offset:64
	global_load_dword v146, v136, s[12:13] offset:128
	global_load_dword v147, v136, s[12:13] offset:192
	global_load_dword v148, v137, s[12:13]
	global_load_dword v149, v137, s[12:13] offset:64
	global_load_dword v150, v137, s[12:13] offset:128
	global_load_dword v151, v137, s[12:13] offset:192
	global_load_dword v152, v143, s[12:13]
	global_load_dword v153, v143, s[12:13] offset:64
	global_load_dword v154, v143, s[12:13] offset:128
	global_load_dword v155, v143, s[12:13] offset:192
	global_load_dword v232, v3, s[12:13]
	global_load_dword v233, v3, s[12:13] offset:64
	global_load_dword v234, v3, s[12:13] offset:128
	global_load_dword v235, v3, s[12:13] offset:192
	s_waitcnt vmcnt(16)
	v_mul_f32_e32 v32, v32, v141
	v_mul_f32_e32 v28, v28, v140
	v_mul_f32_e32 v24, v24, v139
	v_mul_f32_e32 v20, v20, v138
	v_mul_f32_e32 v33, v33, v141
	v_mul_f32_e32 v29, v29, v140
	v_mul_f32_e32 v25, v25, v139
	v_mul_f32_e32 v21, v21, v138
	v_mul_f32_e32 v34, v34, v141
	v_mul_f32_e32 v30, v30, v140
	v_mul_f32_e32 v26, v26, v139
	v_mul_f32_e32 v22, v22, v138
	v_mul_f32_e32 v35, v35, v141
	v_mul_f32_e32 v31, v31, v140
	v_mul_f32_e32 v27, v27, v139
	v_mul_f32_e32 v23, v23, v138
	v_add_f32_e32 v32, v240, v32
	v_add_f32_e32 v28, v241, v28
	v_add_f32_e32 v24, v242, v24
	v_add_f32_e32 v20, v243, v20
	v_add_f32_e32 v33, v244, v33
	v_add_f32_e32 v29, v245, v29
	v_add_f32_e32 v25, v246, v25
	v_add_f32_e32 v21, v247, v21
	v_add_f32_e32 v34, v248, v34
	v_add_f32_e32 v30, v249, v30
	v_add_f32_e32 v26, v250, v26
	v_add_f32_e32 v22, v251, v22
	v_add_f32_e32 v35, v252, v35
	v_add_f32_e32 v31, v253, v31
	v_add_f32_e32 v27, v254, v27
	v_add_f32_e32 v23, v255, v23
	s_waitcnt vmcnt(0)
; __device__ __forceinline__ void outproj_tile(const Params& p, char* smem, int l, int mt, int nt, int ks) {
;     ...
; #pragma unroll
;     for (int m = 0; m < 8; ++m)
; #pragma unroll
;       for (int j = 0; j < 4; ++j) {
;         int row = row0 + wr * 128 + m * 16 + fq * 4 + j;
;         float* orow = O + (size_t)row * 1024 + nt * 128 + wc * 64 + fr;
; #pragma unroll
;         for (int n = 0; n < 4; ++n) unsafeAtomicAdd(orow + n * 16, gv[n] * acc[m][n][j]);
	v_mul_f32_e32 v16, v16, v141
	v_mul_f32_e32 v12, v12, v140
	v_mul_f32_e32 v8, v8, v139
	v_mul_f32_e32 v4, v4, v138
	v_mul_f32_e32 v17, v17, v141
	v_mul_f32_e32 v13, v13, v140
	v_mul_f32_e32 v9, v9, v139
	v_mul_f32_e32 v5, v5, v138
	v_mul_f32_e32 v18, v18, v141
	v_mul_f32_e32 v14, v14, v140
	v_mul_f32_e32 v10, v10, v139
	v_mul_f32_e32 v6, v6, v138
	v_mul_f32_e32 v19, v19, v141
	v_mul_f32_e32 v15, v15, v140
	v_mul_f32_e32 v11, v11, v139
	v_mul_f32_e32 v7, v7, v138
	v_add_f32_e32 v16, v144, v16
	v_add_f32_e32 v12, v145, v12
	v_add_f32_e32 v8, v146, v8
	v_add_f32_e32 v4, v147, v4
	v_add_f32_e32 v17, v148, v17
	v_add_f32_e32 v13, v149, v13
	v_add_f32_e32 v9, v150, v9
	v_add_f32_e32 v5, v151, v5
	v_add_f32_e32 v18, v152, v18
	v_add_f32_e32 v14, v153, v14
	v_add_f32_e32 v10, v154, v10
	v_add_f32_e32 v6, v155, v6
	v_add_f32_e32 v19, v232, v19
	v_add_f32_e32 v15, v233, v15
	v_add_f32_e32 v11, v234, v11
	v_add_f32_e32 v7, v235, v7
	v_add_u32_e32 v132, 0x0, v142
	global_store_dword v132, v128, s[12:13]
	global_store_dword v132, v124, s[12:13] offset:64
	global_store_dword v132, v120, s[12:13] offset:128
	global_store_dword v132, v116, s[12:13] offset:192
	v_add_u32_e32 v133, 0x1000, v142
	global_store_dword v133, v129, s[12:13]
	global_store_dword v133, v125, s[12:13] offset:64
	global_store_dword v133, v121, s[12:13] offset:128
	global_store_dword v133, v117, s[12:13] offset:192
	v_add_u32_e32 v134, 0x2000, v142
	global_store_dword v134, v130, s[12:13]
	global_store_dword v134, v126, s[12:13] offset:64
	global_store_dword v134, v122, s[12:13] offset:128
	global_store_dword v134, v118, s[12:13] offset:192
	v_add_u32_e32 v135, 0x3000, v142
	global_store_dword v135, v131, s[12:13]
	global_store_dword v135, v127, s[12:13] offset:64
	global_store_dword v135, v123, s[12:13] offset:128
	global_store_dword v135, v119, s[12:13] offset:192
	v_add_u32_e32 v132, 0x10000, v142
	global_store_dword v132, v112, s[12:13]
	global_store_dword v132, v108, s[12:13] offset:64
	global_store_dword v132, v104, s[12:13] offset:128
	global_store_dword v132, v100, s[12:13] offset:192
	v_add_u32_e32 v133, 0x11000, v142
	global_store_dword v133, v113, s[12:13]
	global_store_dword v133, v109, s[12:13] offset:64
	global_store_dword v133, v105, s[12:13] offset:128
	global_store_dword v133, v101, s[12:13] offset:192
	v_add_u32_e32 v134, 0x12000, v142
	global_store_dword v134, v114, s[12:13]
	global_store_dword v134, v110, s[12:13] offset:64
	global_store_dword v134, v106, s[12:13] offset:128
	global_store_dword v134, v102, s[12:13] offset:192
	v_add_u32_e32 v135, 0x13000, v142
	global_store_dword v135, v115, s[12:13]
	global_store_dword v135, v111, s[12:13] offset:64
	global_store_dword v135, v107, s[12:13] offset:128
	global_store_dword v135, v103, s[12:13] offset:192
	v_add_u32_e32 v132, 0x20000, v142
	global_store_dword v132, v96, s[12:13]
	global_store_dword v132, v92, s[12:13] offset:64
	global_store_dword v132, v88, s[12:13] offset:128
	global_store_dword v132, v84, s[12:13] offset:192
	v_add_u32_e32 v133, 0x21000, v142
	global_store_dword v133, v97, s[12:13]
	global_store_dword v133, v93, s[12:13] offset:64
	global_store_dword v133, v89, s[12:13] offset:128
	global_store_dword v133, v85, s[12:13] offset:192
	v_add_u32_e32 v134, 0x22000, v142
	global_store_dword v134, v98, s[12:13]
	global_store_dword v134, v94, s[12:13] offset:64
	global_store_dword v134, v90, s[12:13] offset:128
	global_store_dword v134, v86, s[12:13] offset:192
	v_add_u32_e32 v135, 0x23000, v142
	global_store_dword v135, v99, s[12:13]
	global_store_dword v135, v95, s[12:13] offset:64
	global_store_dword v135, v91, s[12:13] offset:128
	global_store_dword v135, v87, s[12:13] offset:192
	v_add_u32_e32 v132, 0x30000, v142
	global_store_dword v132, v80, s[12:13]
	global_store_dword v132, v76, s[12:13] offset:64
	global_store_dword v132, v72, s[12:13] offset:128
	global_store_dword v132, v68, s[12:13] offset:192
	v_add_u32_e32 v133, 0x31000, v142
	global_store_dword v133, v81, s[12:13]
	global_store_dword v133, v77, s[12:13] offset:64
	global_store_dword v133, v73, s[12:13] offset:128
	global_store_dword v133, v69, s[12:13] offset:192
	v_add_u32_e32 v134, 0x32000, v142
	global_store_dword v134, v82, s[12:13]
	global_store_dword v134, v78, s[12:13] offset:64
	global_store_dword v134, v74, s[12:13] offset:128
	global_store_dword v134, v70, s[12:13] offset:192
	v_add_u32_e32 v135, 0x33000, v142
	global_store_dword v135, v83, s[12:13]
	global_store_dword v135, v79, s[12:13] offset:64
	global_store_dword v135, v75, s[12:13] offset:128
	global_store_dword v135, v71, s[12:13] offset:192
	v_add_u32_e32 v132, 0x40000, v142
	global_store_dword v132, v64, s[12:13]
	global_store_dword v132, v60, s[12:13] offset:64
	global_store_dword v132, v56, s[12:13] offset:128
	global_store_dword v132, v52, s[12:13] offset:192
	v_add_u32_e32 v133, 0x41000, v142
	global_store_dword v133, v65, s[12:13]
	global_store_dword v133, v61, s[12:13] offset:64
	global_store_dword v133, v57, s[12:13] offset:128
	global_store_dword v133, v53, s[12:13] offset:192
	v_add_u32_e32 v134, 0x42000, v142
	global_store_dword v134, v66, s[12:13]
	global_store_dword v134, v62, s[12:13] offset:64
	global_store_dword v134, v58, s[12:13] offset:128
	global_store_dword v134, v54, s[12:13] offset:192
	v_add_u32_e32 v135, 0x43000, v142
	global_store_dword v135, v67, s[12:13]
	global_store_dword v135, v63, s[12:13] offset:64
	global_store_dword v135, v59, s[12:13] offset:128
	global_store_dword v135, v55, s[12:13] offset:192
	v_add_u32_e32 v132, 0x50000, v142
	global_store_dword v132, v48, s[12:13]
	global_store_dword v132, v44, s[12:13] offset:64
; __device__ __forceinline__ void outproj_tile(const Params& p, char* smem, int l, int mt, int nt, int ks) {
;     ...
; #pragma unroll
;     for (int m = 0; m < 8; ++m)
; #pragma unroll
;       for (int j = 0; j < 4; ++j) {
;         int row = row0 + wr * 128 + m * 16 + fq * 4 + j;
;         float* orow = O + (size_t)row * 1024 + nt * 128 + wc * 64 + fr;
; #pragma unroll
;         for (int n = 0; n < 4; ++n) unsafeAtomicAdd(orow + n * 16, gv[n] * acc[m][n][j]);
	global_store_dword v132, v40, s[12:13] offset:128
	global_store_dword v132, v36, s[12:13] offset:192
	v_add_u32_e32 v133, 0x51000, v142
	global_store_dword v133, v49, s[12:13]
	global_store_dword v133, v45, s[12:13] offset:64
	global_store_dword v133, v41, s[12:13] offset:128
	global_store_dword v133, v37, s[12:13] offset:192
	v_add_u32_e32 v134, 0x52000, v142
	global_store_dword v134, v50, s[12:13]
	global_store_dword v134, v46, s[12:13] offset:64
	global_store_dword v134, v42, s[12:13] offset:128
	global_store_dword v134, v38, s[12:13] offset:192
	v_add_u32_e32 v135, 0x53000, v142
	global_store_dword v135, v51, s[12:13]
	global_store_dword v135, v47, s[12:13] offset:64
	global_store_dword v135, v43, s[12:13] offset:128
	global_store_dword v135, v39, s[12:13] offset:192
	v_add_u32_e32 v132, 0x60000, v142
	global_store_dword v132, v32, s[12:13]
	global_store_dword v132, v28, s[12:13] offset:64
	global_store_dword v132, v24, s[12:13] offset:128
	global_store_dword v132, v20, s[12:13] offset:192
	v_add_u32_e32 v133, 0x61000, v142
	global_store_dword v133, v33, s[12:13]
	global_store_dword v133, v29, s[12:13] offset:64
	global_store_dword v133, v25, s[12:13] offset:128
	global_store_dword v133, v21, s[12:13] offset:192
	v_add_u32_e32 v134, 0x62000, v142
	global_store_dword v134, v34, s[12:13]
	global_store_dword v134, v30, s[12:13] offset:64
	global_store_dword v134, v26, s[12:13] offset:128
	global_store_dword v134, v22, s[12:13] offset:192
	v_add_u32_e32 v135, 0x63000, v142
	global_store_dword v135, v35, s[12:13]
	global_store_dword v135, v31, s[12:13] offset:64
	global_store_dword v135, v27, s[12:13] offset:128
	global_store_dword v135, v23, s[12:13] offset:192
	v_add_u32_e32 v132, 0x70000, v142
	global_store_dword v132, v16, s[12:13]
	global_store_dword v132, v12, s[12:13] offset:64
	global_store_dword v132, v8, s[12:13] offset:128
	global_store_dword v132, v4, s[12:13] offset:192
	v_add_u32_e32 v133, 0x71000, v142
	global_store_dword v133, v17, s[12:13]
	global_store_dword v133, v13, s[12:13] offset:64
	global_store_dword v133, v9, s[12:13] offset:128
	global_store_dword v133, v5, s[12:13] offset:192
	v_add_u32_e32 v134, 0x72000, v142
	global_store_dword v134, v18, s[12:13]
	global_store_dword v134, v14, s[12:13] offset:64
	global_store_dword v134, v10, s[12:13] offset:128
	global_store_dword v134, v6, s[12:13] offset:192
	v_add_u32_e32 v135, 0x73000, v142
	global_store_dword v135, v19, s[12:13]
	global_store_dword v135, v15, s[12:13] offset:64
	global_store_dword v135, v11, s[12:13] offset:128
	global_store_dword v135, v7, s[12:13] offset:192
	s_branch .LBB0_1195
.Lp3_atomic:
	v_mul_f32_e32 v0, v128, v141
	global_atomic_add_f32 v[142:143], v0, off
	v_mul_f32_e32 v0, v124, v140
	global_atomic_add_f32 v[142:143], v0, off offset:64
	v_mul_f32_e32 v0, v120, v139
	global_atomic_add_f32 v[142:143], v0, off offset:128
	v_mul_f32_e32 v0, v116, v138
	global_atomic_add_f32 v[142:143], v0, off offset:192
	v_or_b32_e32 v142, 1, v2
	v_ashrrev_i32_e32 v143, 31, v142
	v_lshlrev_b64 v[142:143], 12, v[142:143]
	v_lshl_add_u64 v[142:143], s[12:13], 0, v[142:143]
	v_lshl_add_u64 v[142:143], v[142:143], 0, v[132:133]
	v_lshl_add_u64 v[142:143], v[142:143], 0, v[134:135]
	v_lshl_add_u64 v[142:143], v[142:143], 0, v[136:137]
	v_mul_f32_e32 v0, v129, v141
	global_atomic_add_f32 v[142:143], v0, off
	v_mul_f32_e32 v0, v125, v140
	global_atomic_add_f32 v[142:143], v0, off offset:64
	v_mul_f32_e32 v0, v121, v139
	v_or_b32_e32 v116, 2, v2
	global_atomic_add_f32 v[142:143], v0, off offset:128
	v_mul_f32_e32 v0, v117, v138
	v_ashrrev_i32_e32 v117, 31, v116
	v_lshlrev_b64 v[116:117], 12, v[116:117]
	v_lshl_add_u64 v[116:117], s[12:13], 0, v[116:117]
	v_lshl_add_u64 v[116:117], v[116:117], 0, v[132:133]
	v_lshl_add_u64 v[116:117], v[116:117], 0, v[134:135]
	global_atomic_add_f32 v[142:143], v0, off offset:192
	v_lshl_add_u64 v[116:117], v[116:117], 0, v[136:137]
	v_mul_f32_e32 v0, v130, v141
	global_atomic_add_f32 v[116:117], v0, off
	v_mul_f32_e32 v0, v126, v140
	global_atomic_add_f32 v[116:117], v0, off offset:64
	v_mul_f32_e32 v0, v122, v139
	global_atomic_add_f32 v[116:117], v0, off offset:128
	v_mul_f32_e32 v0, v118, v138
	global_atomic_add_f32 v[116:117], v0, off offset:192
	v_or_b32_e32 v116, 3, v2
	v_ashrrev_i32_e32 v117, 31, v116
	v_lshlrev_b64 v[116:117], 12, v[116:117]
	v_lshl_add_u64 v[116:117], s[12:13], 0, v[116:117]
	v_lshl_add_u64 v[116:117], v[116:117], 0, v[132:133]
	v_lshl_add_u64 v[116:117], v[116:117], 0, v[134:135]
	v_lshl_add_u64 v[116:117], v[116:117], 0, v[136:137]
	v_mul_f32_e32 v0, v131, v141
	global_atomic_add_f32 v[116:117], v0, off
	v_mul_f32_e32 v0, v127, v140
	global_atomic_add_f32 v[116:117], v0, off offset:64
	v_mul_f32_e32 v0, v123, v139
	global_atomic_add_f32 v[116:117], v0, off offset:128
	v_mul_f32_e32 v0, v119, v138
	global_atomic_add_f32 v[116:117], v0, off offset:192
	v_or_b32_e32 v116, 16, v2
	v_ashrrev_i32_e32 v117, 31, v116
	v_lshlrev_b64 v[116:117], 12, v[116:117]
	v_lshl_add_u64 v[116:117], s[12:13], 0, v[116:117]
	v_lshl_add_u64 v[116:117], v[116:117], 0, v[132:133]
	v_lshl_add_u64 v[116:117], v[116:117], 0, v[134:135]
	v_lshl_add_u64 v[116:117], v[116:117], 0, v[136:137]
	v_mul_f32_e32 v0, v112, v141
	global_atomic_add_f32 v[116:117], v0, off
	v_mul_f32_e32 v0, v108, v140
	global_atomic_add_f32 v[116:117], v0, off offset:64
	v_mul_f32_e32 v0, v104, v139
	global_atomic_add_f32 v[116:117], v0, off offset:128
	v_mul_f32_e32 v0, v100, v138
	global_atomic_add_f32 v[116:117], v0, off offset:192
	v_or_b32_e32 v116, 17, v2
	v_ashrrev_i32_e32 v117, 31, v116
	v_lshlrev_b64 v[116:117], 12, v[116:117]
; __device__ __forceinline__ void outproj_tile(const Params& p, char* smem, int l, int mt, int nt, int ks) {
;     ...
; #pragma unroll
;     for (int m = 0; m < 8; ++m)
; #pragma unroll
;       for (int j = 0; j < 4; ++j) {
;         int row = row0 + wr * 128 + m * 16 + fq * 4 + j;
;         float* orow = O + (size_t)row * 1024 + nt * 128 + wc * 64 + fr;
; #pragma unroll
;         for (int n = 0; n < 4; ++n) unsafeAtomicAdd(orow + n * 16, gv[n] * acc[m][n][j]);
	v_lshl_add_u64 v[116:117], s[12:13], 0, v[116:117]
	v_lshl_add_u64 v[116:117], v[116:117], 0, v[132:133]
	v_lshl_add_u64 v[116:117], v[116:117], 0, v[134:135]
	v_lshl_add_u64 v[116:117], v[116:117], 0, v[136:137]
	v_mul_f32_e32 v0, v113, v141
	global_atomic_add_f32 v[116:117], v0, off
	v_mul_f32_e32 v0, v109, v140
	global_atomic_add_f32 v[116:117], v0, off offset:64
	v_mul_f32_e32 v0, v105, v139
	v_or_b32_e32 v100, 18, v2
	global_atomic_add_f32 v[116:117], v0, off offset:128
	v_mul_f32_e32 v0, v101, v138
	v_ashrrev_i32_e32 v101, 31, v100
	v_lshlrev_b64 v[100:101], 12, v[100:101]
	v_lshl_add_u64 v[100:101], s[12:13], 0, v[100:101]
	v_lshl_add_u64 v[100:101], v[100:101], 0, v[132:133]
	v_lshl_add_u64 v[100:101], v[100:101], 0, v[134:135]
	global_atomic_add_f32 v[116:117], v0, off offset:192
	v_lshl_add_u64 v[100:101], v[100:101], 0, v[136:137]
	v_mul_f32_e32 v0, v114, v141
	global_atomic_add_f32 v[100:101], v0, off
	v_mul_f32_e32 v0, v110, v140
	global_atomic_add_f32 v[100:101], v0, off offset:64
	v_mul_f32_e32 v0, v106, v139
	global_atomic_add_f32 v[100:101], v0, off offset:128
	v_mul_f32_e32 v0, v102, v138
	global_atomic_add_f32 v[100:101], v0, off offset:192
	v_or_b32_e32 v100, 19, v2
	v_ashrrev_i32_e32 v101, 31, v100
	v_lshlrev_b64 v[100:101], 12, v[100:101]
	v_lshl_add_u64 v[100:101], s[12:13], 0, v[100:101]
	v_lshl_add_u64 v[100:101], v[100:101], 0, v[132:133]
	v_lshl_add_u64 v[100:101], v[100:101], 0, v[134:135]
	v_lshl_add_u64 v[100:101], v[100:101], 0, v[136:137]
	v_mul_f32_e32 v0, v115, v141
	global_atomic_add_f32 v[100:101], v0, off
	v_mul_f32_e32 v0, v111, v140
	global_atomic_add_f32 v[100:101], v0, off offset:64
	v_mul_f32_e32 v0, v107, v139
	global_atomic_add_f32 v[100:101], v0, off offset:128
	v_mul_f32_e32 v0, v103, v138
	global_atomic_add_f32 v[100:101], v0, off offset:192
	v_or_b32_e32 v100, 32, v2
	v_ashrrev_i32_e32 v101, 31, v100
	v_lshlrev_b64 v[100:101], 12, v[100:101]
	v_lshl_add_u64 v[100:101], s[12:13], 0, v[100:101]
	v_lshl_add_u64 v[100:101], v[100:101], 0, v[132:133]
	v_lshl_add_u64 v[100:101], v[100:101], 0, v[134:135]
	v_lshl_add_u64 v[100:101], v[100:101], 0, v[136:137]
	v_mul_f32_e32 v0, v96, v141
	global_atomic_add_f32 v[100:101], v0, off
	v_mul_f32_e32 v0, v92, v140
	global_atomic_add_f32 v[100:101], v0, off offset:64
	v_mul_f32_e32 v0, v88, v139
	global_atomic_add_f32 v[100:101], v0, off offset:128
	v_mul_f32_e32 v0, v84, v138
	global_atomic_add_f32 v[100:101], v0, off offset:192
	v_or_b32_e32 v100, 33, v2
	v_ashrrev_i32_e32 v101, 31, v100
	v_lshlrev_b64 v[100:101], 12, v[100:101]
	v_lshl_add_u64 v[100:101], s[12:13], 0, v[100:101]
	v_lshl_add_u64 v[100:101], v[100:101], 0, v[132:133]
	v_lshl_add_u64 v[100:101], v[100:101], 0, v[134:135]
	v_lshl_add_u64 v[100:101], v[100:101], 0, v[136:137]
	v_mul_f32_e32 v0, v97, v141
	global_atomic_add_f32 v[100:101], v0, off
	v_mul_f32_e32 v0, v93, v140
	global_atomic_add_f32 v[100:101], v0, off offset:64
	v_mul_f32_e32 v0, v89, v139
	v_or_b32_e32 v84, 34, v2
	global_atomic_add_f32 v[100:101], v0, off offset:128
	v_mul_f32_e32 v0, v85, v138
	v_ashrrev_i32_e32 v85, 31, v84
	v_lshlrev_b64 v[84:85], 12, v[84:85]
	v_lshl_add_u64 v[84:85], s[12:13], 0, v[84:85]
	v_lshl_add_u64 v[84:85], v[84:85], 0, v[132:133]
	v_lshl_add_u64 v[84:85], v[84:85], 0, v[134:135]
	global_atomic_add_f32 v[100:101], v0, off offset:192
	v_lshl_add_u64 v[84:85], v[84:85], 0, v[136:137]
	v_mul_f32_e32 v0, v98, v141
	global_atomic_add_f32 v[84:85], v0, off
	v_mul_f32_e32 v0, v94, v140
	global_atomic_add_f32 v[84:85], v0, off offset:64
	v_mul_f32_e32 v0, v90, v139
	global_atomic_add_f32 v[84:85], v0, off offset:128
	v_mul_f32_e32 v0, v86, v138
	global_atomic_add_f32 v[84:85], v0, off offset:192
	v_or_b32_e32 v84, 35, v2
	v_ashrrev_i32_e32 v85, 31, v84
	v_lshlrev_b64 v[84:85], 12, v[84:85]
	v_lshl_add_u64 v[84:85], s[12:13], 0, v[84:85]
	v_lshl_add_u64 v[84:85], v[84:85], 0, v[132:133]
	v_lshl_add_u64 v[84:85], v[84:85], 0, v[134:135]
	v_lshl_add_u64 v[84:85], v[84:85], 0, v[136:137]
	v_mul_f32_e32 v0, v99, v141
	global_atomic_add_f32 v[84:85], v0, off
	v_mul_f32_e32 v0, v95, v140
	global_atomic_add_f32 v[84:85], v0, off offset:64
	v_mul_f32_e32 v0, v91, v139
	global_atomic_add_f32 v[84:85], v0, off offset:128
	v_mul_f32_e32 v0, v87, v138
	global_atomic_add_f32 v[84:85], v0, off offset:192
	v_or_b32_e32 v84, 48, v2
	v_ashrrev_i32_e32 v85, 31, v84
	v_lshlrev_b64 v[84:85], 12, v[84:85]
	v_lshl_add_u64 v[84:85], s[12:13], 0, v[84:85]
	v_lshl_add_u64 v[84:85], v[84:85], 0, v[132:133]
	v_lshl_add_u64 v[84:85], v[84:85], 0, v[134:135]
	v_lshl_add_u64 v[84:85], v[84:85], 0, v[136:137]
	v_mul_f32_e32 v0, v80, v141
	global_atomic_add_f32 v[84:85], v0, off
	v_mul_f32_e32 v0, v76, v140
	global_atomic_add_f32 v[84:85], v0, off offset:64
	v_mul_f32_e32 v0, v72, v139
	global_atomic_add_f32 v[84:85], v0, off offset:128
	v_mul_f32_e32 v0, v68, v138
	global_atomic_add_f32 v[84:85], v0, off offset:192
	v_or_b32_e32 v84, 49, v2
	v_ashrrev_i32_e32 v85, 31, v84
	v_lshlrev_b64 v[84:85], 12, v[84:85]
	v_lshl_add_u64 v[84:85], s[12:13], 0, v[84:85]
	v_lshl_add_u64 v[84:85], v[84:85], 0, v[132:133]
	v_lshl_add_u64 v[84:85], v[84:85], 0, v[134:135]
	v_lshl_add_u64 v[84:85], v[84:85], 0, v[136:137]
	v_mul_f32_e32 v0, v81, v141
	global_atomic_add_f32 v[84:85], v0, off
	v_mul_f32_e32 v0, v77, v140
	global_atomic_add_f32 v[84:85], v0, off offset:64
	v_mul_f32_e32 v0, v73, v139
	v_or_b32_e32 v68, 50, v2
	global_atomic_add_f32 v[84:85], v0, off offset:128
	v_mul_f32_e32 v0, v69, v138
	v_ashrrev_i32_e32 v69, 31, v68
	v_lshlrev_b64 v[68:69], 12, v[68:69]
	v_lshl_add_u64 v[68:69], s[12:13], 0, v[68:69]
	v_lshl_add_u64 v[68:69], v[68:69], 0, v[132:133]
; __device__ __forceinline__ void outproj_tile(const Params& p, char* smem, int l, int mt, int nt, int ks) {
;     ...
; #pragma unroll
;     for (int m = 0; m < 8; ++m)
; #pragma unroll
;       for (int j = 0; j < 4; ++j) {
;         int row = row0 + wr * 128 + m * 16 + fq * 4 + j;
;         float* orow = O + (size_t)row * 1024 + nt * 128 + wc * 64 + fr;
; #pragma unroll
;         for (int n = 0; n < 4; ++n) unsafeAtomicAdd(orow + n * 16, gv[n] * acc[m][n][j]);
	v_lshl_add_u64 v[68:69], v[68:69], 0, v[134:135]
	global_atomic_add_f32 v[84:85], v0, off offset:192
	v_lshl_add_u64 v[68:69], v[68:69], 0, v[136:137]
	v_mul_f32_e32 v0, v82, v141
	global_atomic_add_f32 v[68:69], v0, off
	v_mul_f32_e32 v0, v78, v140
	global_atomic_add_f32 v[68:69], v0, off offset:64
	v_mul_f32_e32 v0, v74, v139
	global_atomic_add_f32 v[68:69], v0, off offset:128
	v_mul_f32_e32 v0, v70, v138
	global_atomic_add_f32 v[68:69], v0, off offset:192
	v_or_b32_e32 v68, 51, v2
	v_ashrrev_i32_e32 v69, 31, v68
	v_lshlrev_b64 v[68:69], 12, v[68:69]
	v_lshl_add_u64 v[68:69], s[12:13], 0, v[68:69]
	v_lshl_add_u64 v[68:69], v[68:69], 0, v[132:133]
	v_lshl_add_u64 v[68:69], v[68:69], 0, v[134:135]
	v_lshl_add_u64 v[68:69], v[68:69], 0, v[136:137]
	v_mul_f32_e32 v0, v83, v141
	global_atomic_add_f32 v[68:69], v0, off
	v_mul_f32_e32 v0, v79, v140
	global_atomic_add_f32 v[68:69], v0, off offset:64
	v_mul_f32_e32 v0, v75, v139
	global_atomic_add_f32 v[68:69], v0, off offset:128
	v_mul_f32_e32 v0, v71, v138
	global_atomic_add_f32 v[68:69], v0, off offset:192
	v_or_b32_e32 v68, 64, v2
	v_ashrrev_i32_e32 v69, 31, v68
	v_lshlrev_b64 v[68:69], 12, v[68:69]
	v_lshl_add_u64 v[68:69], s[12:13], 0, v[68:69]
	v_lshl_add_u64 v[68:69], v[68:69], 0, v[132:133]
	v_lshl_add_u64 v[68:69], v[68:69], 0, v[134:135]
	v_lshl_add_u64 v[68:69], v[68:69], 0, v[136:137]
	v_mul_f32_e32 v0, v64, v141
	global_atomic_add_f32 v[68:69], v0, off
	v_mul_f32_e32 v0, v60, v140
	global_atomic_add_f32 v[68:69], v0, off offset:64
	v_mul_f32_e32 v0, v56, v139
	global_atomic_add_f32 v[68:69], v0, off offset:128
	v_mul_f32_e32 v0, v52, v138
	global_atomic_add_f32 v[68:69], v0, off offset:192
	v_or_b32_e32 v68, 0x41, v2
	v_ashrrev_i32_e32 v69, 31, v68
	v_lshlrev_b64 v[68:69], 12, v[68:69]
	v_lshl_add_u64 v[68:69], s[12:13], 0, v[68:69]
	v_lshl_add_u64 v[68:69], v[68:69], 0, v[132:133]
	v_lshl_add_u64 v[68:69], v[68:69], 0, v[134:135]
	v_lshl_add_u64 v[68:69], v[68:69], 0, v[136:137]
	v_mul_f32_e32 v0, v65, v141
	global_atomic_add_f32 v[68:69], v0, off
	v_mul_f32_e32 v0, v61, v140
	global_atomic_add_f32 v[68:69], v0, off offset:64
	v_mul_f32_e32 v0, v57, v139
	v_or_b32_e32 v52, 0x42, v2
	global_atomic_add_f32 v[68:69], v0, off offset:128
	v_mul_f32_e32 v0, v53, v138
	v_ashrrev_i32_e32 v53, 31, v52
	v_lshlrev_b64 v[52:53], 12, v[52:53]
	v_lshl_add_u64 v[52:53], s[12:13], 0, v[52:53]
	v_lshl_add_u64 v[52:53], v[52:53], 0, v[132:133]
	v_lshl_add_u64 v[52:53], v[52:53], 0, v[134:135]
	global_atomic_add_f32 v[68:69], v0, off offset:192
	v_lshl_add_u64 v[52:53], v[52:53], 0, v[136:137]
	v_mul_f32_e32 v0, v66, v141
	global_atomic_add_f32 v[52:53], v0, off
	v_mul_f32_e32 v0, v62, v140
	global_atomic_add_f32 v[52:53], v0, off offset:64
	v_mul_f32_e32 v0, v58, v139
	global_atomic_add_f32 v[52:53], v0, off offset:128
	v_mul_f32_e32 v0, v54, v138
	global_atomic_add_f32 v[52:53], v0, off offset:192
	v_or_b32_e32 v52, 0x43, v2
	v_ashrrev_i32_e32 v53, 31, v52
	v_lshlrev_b64 v[52:53], 12, v[52:53]
	v_lshl_add_u64 v[52:53], s[12:13], 0, v[52:53]
	v_lshl_add_u64 v[52:53], v[52:53], 0, v[132:133]
	v_lshl_add_u64 v[52:53], v[52:53], 0, v[134:135]
	v_lshl_add_u64 v[52:53], v[52:53], 0, v[136:137]
	v_mul_f32_e32 v0, v67, v141
	global_atomic_add_f32 v[52:53], v0, off
	v_mul_f32_e32 v0, v63, v140
	global_atomic_add_f32 v[52:53], v0, off offset:64
	v_mul_f32_e32 v0, v59, v139
	global_atomic_add_f32 v[52:53], v0, off offset:128
	v_mul_f32_e32 v0, v55, v138
	global_atomic_add_f32 v[52:53], v0, off offset:192
	v_or_b32_e32 v52, 0x50, v2
	v_ashrrev_i32_e32 v53, 31, v52
	v_lshlrev_b64 v[52:53], 12, v[52:53]
	v_lshl_add_u64 v[52:53], s[12:13], 0, v[52:53]
	v_lshl_add_u64 v[52:53], v[52:53], 0, v[132:133]
	v_lshl_add_u64 v[52:53], v[52:53], 0, v[134:135]
	v_lshl_add_u64 v[52:53], v[52:53], 0, v[136:137]
	v_mul_f32_e32 v0, v48, v141
	global_atomic_add_f32 v[52:53], v0, off
	v_mul_f32_e32 v0, v44, v140
	global_atomic_add_f32 v[52:53], v0, off offset:64
	v_mul_f32_e32 v0, v40, v139
	global_atomic_add_f32 v[52:53], v0, off offset:128
	v_mul_f32_e32 v0, v36, v138
	global_atomic_add_f32 v[52:53], v0, off offset:192
	v_or_b32_e32 v52, 0x51, v2
	v_ashrrev_i32_e32 v53, 31, v52
	v_lshlrev_b64 v[52:53], 12, v[52:53]
	v_lshl_add_u64 v[52:53], s[12:13], 0, v[52:53]
	v_lshl_add_u64 v[52:53], v[52:53], 0, v[132:133]
	v_lshl_add_u64 v[52:53], v[52:53], 0, v[134:135]
	v_lshl_add_u64 v[52:53], v[52:53], 0, v[136:137]
	v_mul_f32_e32 v0, v49, v141
	global_atomic_add_f32 v[52:53], v0, off
	v_mul_f32_e32 v0, v45, v140
	global_atomic_add_f32 v[52:53], v0, off offset:64
	v_mul_f32_e32 v0, v41, v139
	v_or_b32_e32 v36, 0x52, v2
	global_atomic_add_f32 v[52:53], v0, off offset:128
	v_mul_f32_e32 v0, v37, v138
	v_ashrrev_i32_e32 v37, 31, v36
	v_lshlrev_b64 v[36:37], 12, v[36:37]
	v_lshl_add_u64 v[36:37], s[12:13], 0, v[36:37]
	v_lshl_add_u64 v[36:37], v[36:37], 0, v[132:133]
	v_lshl_add_u64 v[36:37], v[36:37], 0, v[134:135]
	global_atomic_add_f32 v[52:53], v0, off offset:192
	v_lshl_add_u64 v[36:37], v[36:37], 0, v[136:137]
	v_mul_f32_e32 v0, v50, v141
	global_atomic_add_f32 v[36:37], v0, off
	v_mul_f32_e32 v0, v46, v140
	global_atomic_add_f32 v[36:37], v0, off offset:64
	v_mul_f32_e32 v0, v42, v139
	global_atomic_add_f32 v[36:37], v0, off offset:128
	v_mul_f32_e32 v0, v38, v138
	global_atomic_add_f32 v[36:37], v0, off offset:192
	v_or_b32_e32 v36, 0x53, v2
; __device__ __forceinline__ void outproj_tile(const Params& p, char* smem, int l, int mt, int nt, int ks) {
;     ...
; #pragma unroll
;     for (int m = 0; m < 8; ++m)
; #pragma unroll
;       for (int j = 0; j < 4; ++j) {
;         int row = row0 + wr * 128 + m * 16 + fq * 4 + j;
;         float* orow = O + (size_t)row * 1024 + nt * 128 + wc * 64 + fr;
; #pragma unroll
;         for (int n = 0; n < 4; ++n) unsafeAtomicAdd(orow + n * 16, gv[n] * acc[m][n][j]);
	v_ashrrev_i32_e32 v37, 31, v36
	v_lshlrev_b64 v[36:37], 12, v[36:37]
	v_lshl_add_u64 v[36:37], s[12:13], 0, v[36:37]
	v_lshl_add_u64 v[36:37], v[36:37], 0, v[132:133]
	v_lshl_add_u64 v[36:37], v[36:37], 0, v[134:135]
	v_lshl_add_u64 v[36:37], v[36:37], 0, v[136:137]
	v_mul_f32_e32 v0, v51, v141
	global_atomic_add_f32 v[36:37], v0, off
	v_mul_f32_e32 v0, v47, v140
	global_atomic_add_f32 v[36:37], v0, off offset:64
	v_mul_f32_e32 v0, v43, v139
	global_atomic_add_f32 v[36:37], v0, off offset:128
	v_mul_f32_e32 v0, v39, v138
	global_atomic_add_f32 v[36:37], v0, off offset:192
	v_or_b32_e32 v36, 0x60, v2
	v_ashrrev_i32_e32 v37, 31, v36
	v_lshlrev_b64 v[36:37], 12, v[36:37]
	v_lshl_add_u64 v[36:37], s[12:13], 0, v[36:37]
	v_lshl_add_u64 v[36:37], v[36:37], 0, v[132:133]
	v_lshl_add_u64 v[36:37], v[36:37], 0, v[134:135]
	v_lshl_add_u64 v[36:37], v[36:37], 0, v[136:137]
	v_mul_f32_e32 v0, v32, v141
	global_atomic_add_f32 v[36:37], v0, off
	v_mul_f32_e32 v0, v28, v140
	global_atomic_add_f32 v[36:37], v0, off offset:64
	v_mul_f32_e32 v0, v24, v139
	global_atomic_add_f32 v[36:37], v0, off offset:128
	v_mul_f32_e32 v0, v20, v138
	global_atomic_add_f32 v[36:37], v0, off offset:192
	v_or_b32_e32 v36, 0x61, v2
	v_ashrrev_i32_e32 v37, 31, v36
	v_lshlrev_b64 v[36:37], 12, v[36:37]
	v_lshl_add_u64 v[36:37], s[12:13], 0, v[36:37]
	v_lshl_add_u64 v[36:37], v[36:37], 0, v[132:133]
	v_lshl_add_u64 v[36:37], v[36:37], 0, v[134:135]
	v_lshl_add_u64 v[36:37], v[36:37], 0, v[136:137]
	v_mul_f32_e32 v0, v33, v141
	global_atomic_add_f32 v[36:37], v0, off
	v_mul_f32_e32 v0, v29, v140
	global_atomic_add_f32 v[36:37], v0, off offset:64
	v_mul_f32_e32 v0, v25, v139
	v_or_b32_e32 v20, 0x62, v2
	global_atomic_add_f32 v[36:37], v0, off offset:128
	v_mul_f32_e32 v0, v21, v138
	v_ashrrev_i32_e32 v21, 31, v20
	v_lshlrev_b64 v[20:21], 12, v[20:21]
	v_lshl_add_u64 v[20:21], s[12:13], 0, v[20:21]
	v_lshl_add_u64 v[20:21], v[20:21], 0, v[132:133]
	v_lshl_add_u64 v[20:21], v[20:21], 0, v[134:135]
	global_atomic_add_f32 v[36:37], v0, off offset:192
	v_lshl_add_u64 v[20:21], v[20:21], 0, v[136:137]
	v_mul_f32_e32 v0, v34, v141
	global_atomic_add_f32 v[20:21], v0, off
	v_mul_f32_e32 v0, v30, v140
	global_atomic_add_f32 v[20:21], v0, off offset:64
	v_mul_f32_e32 v0, v26, v139
	global_atomic_add_f32 v[20:21], v0, off offset:128
	v_mul_f32_e32 v0, v22, v138
	global_atomic_add_f32 v[20:21], v0, off offset:192
	v_or_b32_e32 v20, 0x63, v2
	v_ashrrev_i32_e32 v21, 31, v20
	v_lshlrev_b64 v[20:21], 12, v[20:21]
	v_lshl_add_u64 v[20:21], s[12:13], 0, v[20:21]
	v_lshl_add_u64 v[20:21], v[20:21], 0, v[132:133]
	v_lshl_add_u64 v[20:21], v[20:21], 0, v[134:135]
	v_lshl_add_u64 v[20:21], v[20:21], 0, v[136:137]
	v_mul_f32_e32 v0, v35, v141
	global_atomic_add_f32 v[20:21], v0, off
	v_mul_f32_e32 v0, v31, v140
	global_atomic_add_f32 v[20:21], v0, off offset:64
	v_mul_f32_e32 v0, v27, v139
	global_atomic_add_f32 v[20:21], v0, off offset:128
	v_mul_f32_e32 v0, v23, v138
	global_atomic_add_f32 v[20:21], v0, off offset:192
	v_or_b32_e32 v20, 0x70, v2
	v_ashrrev_i32_e32 v21, 31, v20
	v_lshlrev_b64 v[20:21], 12, v[20:21]
	v_lshl_add_u64 v[20:21], s[12:13], 0, v[20:21]
	v_lshl_add_u64 v[20:21], v[20:21], 0, v[132:133]
	v_lshl_add_u64 v[20:21], v[20:21], 0, v[134:135]
	v_lshl_add_u64 v[20:21], v[20:21], 0, v[136:137]
	v_mul_f32_e32 v0, v16, v141
	global_atomic_add_f32 v[20:21], v0, off
	v_mul_f32_e32 v0, v12, v140
	global_atomic_add_f32 v[20:21], v0, off offset:64
	v_mul_f32_e32 v0, v8, v139
	global_atomic_add_f32 v[20:21], v0, off offset:128
	v_mul_f32_e32 v0, v4, v138
	global_atomic_add_f32 v[20:21], v0, off offset:192
	v_or_b32_e32 v20, 0x71, v2
	v_ashrrev_i32_e32 v21, 31, v20
	v_lshlrev_b64 v[20:21], 12, v[20:21]
	v_lshl_add_u64 v[20:21], s[12:13], 0, v[20:21]
	v_lshl_add_u64 v[20:21], v[20:21], 0, v[132:133]
	v_lshl_add_u64 v[20:21], v[20:21], 0, v[134:135]
	v_lshl_add_u64 v[20:21], v[20:21], 0, v[136:137]
	v_mul_f32_e32 v0, v17, v141
	global_atomic_add_f32 v[20:21], v0, off
	v_mul_f32_e32 v0, v13, v140
	global_atomic_add_f32 v[20:21], v0, off offset:64
	v_mul_f32_e32 v0, v9, v139
	v_or_b32_e32 v4, 0x72, v2
	global_atomic_add_f32 v[20:21], v0, off offset:128
	v_mul_f32_e32 v0, v5, v138
	v_ashrrev_i32_e32 v5, 31, v4
	v_lshlrev_b64 v[4:5], 12, v[4:5]
	v_lshl_add_u64 v[4:5], s[12:13], 0, v[4:5]
	v_lshl_add_u64 v[4:5], v[4:5], 0, v[132:133]
	v_or_b32_e32 v2, 0x73, v2
	v_lshl_add_u64 v[4:5], v[4:5], 0, v[134:135]
	v_ashrrev_i32_e32 v3, 31, v2
	global_atomic_add_f32 v[20:21], v0, off offset:192
	v_lshl_add_u64 v[4:5], v[4:5], 0, v[136:137]
	v_mul_f32_e32 v0, v18, v141
	v_lshlrev_b64 v[2:3], 12, v[2:3]
	global_atomic_add_f32 v[4:5], v0, off
	v_mul_f32_e32 v0, v14, v140
	v_lshl_add_u64 v[2:3], s[12:13], 0, v[2:3]
	global_atomic_add_f32 v[4:5], v0, off offset:64
	v_mul_f32_e32 v0, v10, v139
	v_lshl_add_u64 v[2:3], v[2:3], 0, v[132:133]
	global_atomic_add_f32 v[4:5], v0, off offset:128
	v_mul_f32_e32 v0, v6, v138
	v_lshl_add_u64 v[2:3], v[2:3], 0, v[134:135]
	global_atomic_add_f32 v[4:5], v0, off offset:192
	v_lshl_add_u64 v[2:3], v[2:3], 0, v[136:137]
	v_mul_f32_e32 v0, v19, v141
	global_atomic_add_f32 v[2:3], v0, off
	v_mul_f32_e32 v0, v15, v140
	global_atomic_add_f32 v[2:3], v0, off offset:64
	v_mul_f32_e32 v0, v11, v139
	global_atomic_add_f32 v[2:3], v0, off offset:128
	v_mul_f32_e32 v0, v7, v138
	global_atomic_add_f32 v[2:3], v0, off offset:192
